# mixer queue: attention items taken longest-first (256-row T=4096 items, then 128-row T=4096, then T=2048, shortest last) via index remap; no stagger
# baseline (speedup 1.0000x reference)
.LBB0_336:
	s_or_b64 exec, exec, s[4:5]
	s_waitcnt lgkmcnt(0)
	s_barrier
	s_waitcnt vmcnt(2)
	ds_read_b32 v0, v177
	s_waitcnt lgkmcnt(0)
	v_cmp_gt_i32_e32 vcc, 0, v0
	v_readfirstlane_b32 s18, v0
	s_cbranch_vccnz .LBB0_344
	s_and_b32 s14, s18, 0xffff
	s_cmp_lt_u32 s14, 32
	s_cbranch_scc1 .Lmx_noremap
	s_sub_i32 s14, s14, 32
	s_cmpk_lt_u32 s14, 0x100
	s_cselect_b32 s15, 0x80, 64
	s_xor_b32 s14, s14, s15
	s_add_i32 s14, s14, 32
	s_and_b32 s18, s18, 0xffff0000
	s_or_b32 s18, s18, s14
.Lmx_noremap:
	s_lshr_b32 s19, s18, 16
	s_and_b32 s14, s18, 0xffff
	s_cmp_gt_u32 s14, 31
	s_mov_b64 s[4:5], -1
	s_cbranch_scc0 .LBB0_431
	s_cmpk_gt_u32 s14, 0x9f
	s_cbranch_scc0 .LBB0_422
	s_cmpk_gt_u32 s14, 0xdf
	s_cbranch_scc0 .LBB0_395
	s_cmpk_gt_u32 s14, 0x11f
	s_cbranch_scc0 .LBB0_386
	s_add_i32 s15, s19, 8
	s_cmpk_gt_u32 s14, 0x15f
	s_cbranch_scc0 .LBB0_377
	s_and_b32 s8, s18, 7
	s_cmpk_gt_u32 s14, 0x17f
	s_cbranch_scc0 .LBB0_351
	s_add_i32 s4, s14, 0xfffffe80
	v_readlane_b32 s6, v254, 57
	s_lshr_b32 s5, s4, 3
	s_waitcnt vmcnt(1)
	v_mov_b32_e32 v4, v179
	s_mov_b32 s4, s6
	v_readlane_b32 s7, v254, 58
	s_mov_b32 s6, s15
	s_mov_b32 s7, s8
	s_lshl_b32 s4, s6, 11
	s_add_i32 s9, s4, 0x4000
	s_lshl_b32 s10, s6, 12
	s_lshl_b32 s4, s5, 6
	s_lshl_b32 s11, s5, 5
	s_lshl_b32 s5, s7, 8
	s_cmp_lt_i32 s6, 8
	s_cselect_b32 s10, s10, s9
	v_and_b32_e32 v0, 0xffffffdf, v4
	s_cselect_b32 s9, 64, 32
	s_add_i32 s5, s10, s5
	v_add_u32_e32 v6, s5, v0
	s_ashr_i32 s5, s4, 31
	s_lshl_b64 s[4:5], s[4:5], 1
	v_bfe_u32 v192, v4, 5, 1
	s_add_u32 s6, s78, s4
	s_addc_u32 s7, s79, s5
	v_lshlrev_b32_e32 v176, 4, v192
	v_lshl_add_u64 v[0:1], s[6:7], 0, v[176:177]
	v_mad_i64_i32 v[2:3], s[6:7], v6, s67, v[0:1]
	global_load_dwordx4 v[128:131], v[2:3], off
	global_load_dwordx4 v[132:135], v[2:3], off offset:32
	global_load_dwordx4 v[136:139], v[2:3], off offset:64
	global_load_dwordx4 v[140:143], v[2:3], off offset:96
	v_or_b32_e32 v2, 32, v6
	v_mad_i64_i32 v[182:183], s[6:7], v6, s67, 0
	v_mad_i64_i32 v[0:1], s[6:7], v2, s67, v[0:1]
	v_ashrrev_i32_e32 v6, 3, v4
	v_mad_i64_i32 v[180:181], s[6:7], v2, s67, 0
	global_load_dwordx4 v[144:147], v[0:1], off
	global_load_dwordx4 v[148:151], v[0:1], off offset:32
	global_load_dwordx4 v[152:155], v[0:1], off offset:64
	global_load_dwordx4 v[156:159], v[0:1], off offset:96
	v_add_u32_e32 v2, s10, v6
	v_mov_b64_e32 v[0:1], s[78:79]
	v_mad_i64_i32 v[0:1], s[6:7], v2, s67, v[0:1]
	v_lshlrev_b32_e32 v2, 1, v4
	s_and_b32 s6, s11, 0xffffffc0
	v_and_b32_e32 v7, 8, v2
	v_lshrrev_b32_e32 v2, 1, v4
	s_ashr_i32 s7, s6, 31
	s_waitcnt vmcnt(8)
	v_and_b32_e32 v8, 4, v2
	v_lshlrev_b32_e32 v2, 4, v4
	v_lshl_add_u64 v[0:1], s[6:7], 1, v[0:1]
	v_and_b32_e32 v2, 0x70, v2
	v_mov_b32_e32 v3, v177
	v_lshl_add_u64 v[184:185], v[0:1], 0, v[2:3]
	s_mov_b32 s6, 0x35000
	v_add_co_u32_e32 v0, vcc, s6, v184
	global_load_dwordx4 v[160:163], v[184:185], off offset:512
	global_load_dwordx4 v[164:167], v[184:185], off offset:768
	v_addc_co_u32_e32 v1, vcc, 0, v185, vcc
	global_load_dwordx4 v[168:171], v[0:1], off offset:512
	global_load_dwordx4 v[172:175], v[0:1], off offset:768
	s_movk_i32 s6, 0x90
	v_mul_lo_u32 v0, v6, s6
	v_add3_u32 v194, 16, v2, v0
	v_and_b32_e32 v2, 64, v229
	v_and_b32_e32 v3, 19, v4
	v_xor_b32_e32 v1, 32, v229
	v_add_u32_e32 v2, 64, v2
	v_or3_b32 v0, v3, v7, v8
	v_cmp_lt_i32_e32 vcc, v1, v2
	v_and_b32_e32 v5, 31, v4
	v_mul_u32_u24_e32 v195, 0x90, v0
	v_cndmask_b32_e32 v1, v229, v1, vcc
	v_mov_b32_e32 v0, 0
	s_mov_b32 s12, 0
	v_lshlrev_b32_e32 v193, 2, v1
	v_mul_u32_u24_e32 v196, 0x90, v5
	v_add_u32_e32 v197, 16, v176
	v_mov_b32_e32 v188, 0xff800000
	s_movk_i32 s10, 0x60
	v_mov_b32_e32 v176, 0xff800000
	v_mov_b32_e32 v1, v0
	v_mov_b32_e32 v2, v0
	v_mov_b32_e32 v3, v0
	v_mov_b32_e32 v4, v0
	v_mov_b32_e32 v5, v0
	v_mov_b32_e32 v6, v0
	v_mov_b32_e32 v7, v0
	v_mov_b32_e32 v8, v0
	v_mov_b32_e32 v9, v0
	v_mov_b32_e32 v10, v0
	v_mov_b32_e32 v11, v0
	v_mov_b32_e32 v12, v0
	v_mov_b32_e32 v13, v0
	v_mov_b32_e32 v14, v0
	v_mov_b32_e32 v15, v0
	v_mov_b32_e32 v16, v0
	v_mov_b32_e32 v17, v0
	v_mov_b32_e32 v18, v0
	v_mov_b32_e32 v19, v0
	v_mov_b32_e32 v20, v0
	v_mov_b32_e32 v21, v0
	v_mov_b32_e32 v22, v0
	v_mov_b32_e32 v23, v0
	v_mov_b32_e32 v24, v0
	v_mov_b32_e32 v25, v0
	v_mov_b32_e32 v26, v0
	v_mov_b32_e32 v27, v0
	v_mov_b32_e32 v28, v0
	v_mov_b32_e32 v29, v0
	v_mov_b32_e32 v30, v0
	v_mov_b32_e32 v31, v0
	v_mov_b32_e32 v32, v0
	v_mov_b32_e32 v33, v0
	v_mov_b32_e32 v34, v0
	v_mov_b32_e32 v35, v0
	v_mov_b32_e32 v36, v0
	v_mov_b32_e32 v37, v0
	v_mov_b32_e32 v38, v0
	v_mov_b32_e32 v39, v0
	v_mov_b32_e32 v40, v0
	v_mov_b32_e32 v41, v0
	v_mov_b32_e32 v42, v0
	v_mov_b32_e32 v43, v0
	v_mov_b32_e32 v44, v0
	v_mov_b32_e32 v45, v0
	v_mov_b32_e32 v46, v0
	v_mov_b32_e32 v47, v0
	v_mov_b32_e32 v48, v0
	v_mov_b32_e32 v49, v0
	v_mov_b32_e32 v50, v0
	v_mov_b32_e32 v51, v0
	v_mov_b32_e32 v52, v0
	v_mov_b32_e32 v53, v0
	v_mov_b32_e32 v54, v0
	v_mov_b32_e32 v55, v0
	v_mov_b32_e32 v56, v0
	v_mov_b32_e32 v57, v0
	v_mov_b32_e32 v58, v0
	v_mov_b32_e32 v59, v0
	v_mov_b32_e32 v60, v0
	v_mov_b32_e32 v61, v0
	v_mov_b32_e32 v62, v0
	v_mov_b32_e32 v63, v0
	v_mov_b32_e32 v186, v0
	v_mov_b32_e32 v187, v0
	s_waitcnt vmcnt(3)
	ds_write_b128 v194, v[160:163]
	s_waitcnt vmcnt(2)
	ds_write_b128 v194, v[164:167] offset:9216
	s_waitcnt vmcnt(1)
	ds_write_b128 v194, v[168:171] offset:4608
	s_waitcnt vmcnt(0)
	ds_write_b128 v194, v[172:175] offset:13824
	s_waitcnt lgkmcnt(0)
	s_barrier
	s_branch .LBB0_346
